# conv row reductions: xor16/xor32 hops via v_permlane16/32_swap instead of ds_bpermute round trips (bit-identical); on v91
# baseline (speedup 1.0000x reference)
; #define GAS __attribute__((address_space(1)))
; __device__ __forceinline__ float bf_lo(unsigned w) { return __uint_as_float(w << 16); }
; __device__ __forceinline__ float bf_hi(unsigned w) { return __uint_as_float(w & 0xffff0000u); }
; #define CV_U(dst, xv, gv) do { dst[0] = bf_lo(xv.x) * bf_lo(gv.x); dst[1] = bf_hi(xv.x) * bf_hi(gv.x); dst[2] = bf_lo(xv.y) * bf_lo(gv.y); dst[3] = bf_hi(xv.y) * bf_hi(gv.y); \
;         dst[4] = bf_lo(xv.z) * bf_lo(gv.z); dst[5] = bf_hi(xv.z) * bf_hi(gv.z); dst[6] = bf_lo(xv.w) * bf_lo(gv.w); dst[7] = bf_hi(xv.w) * bf_hi(gv.w); } while (0)
; __device__ __forceinline__ void conv_unit(const bf16* PROJ, bf16* YMIX, const float* w_conv, const float* b_conv, const float* g_conv, int b, int c, int wave, int lane_in) {
;     ...
;         const int s0 = c * 64 + 8 * wave;
;         const bf16* rowp = PROJ + ((size_t)b * SEQ + s0) * NPROJ + ch0;
;         u32x4 xa[10], ga[10], gb[8];
; #pragma unroll
;         for (int r = 0; r < 10; ++r) { if (r >= 2 || s0 >= 2) { xa[r] = *(const GAS u32x4*)(rowp + (r - 2) * NPROJ + 1536); ga[r] = *(const GAS u32x4*)(rowp + (r - 2) * NPROJ + 2560); }
;             else { xa[r] = (u32x4){0u, 0u, 0u, 0u}; ga[r] = xa[r]; } }
; #pragma unroll
;         for (int r = 0; r < 8; ++r) gb[r] = __builtin_nontemporal_load((const GAS u32x4*)(rowp + r * NPROJ + 2048));
;     ...
;         float u0[8], u1[8];
;         CV_U(u0, xa[0], ga[0]); CV_U(u1, xa[1], ga[1]);
; #pragma unroll
;         for (int r = 0; r < 8; ++r) {
;             float u2[8]; CV_U(u2, xa[r + 2], ga[r + 2]);
;             const u32x4 gbv = gb[r];
;             float gbf[8] = {bf_lo(gbv.x), bf_hi(gbv.x), bf_lo(gbv.y), bf_hi(gbv.y), bf_lo(gbv.z), bf_hi(gbv.z), bf_lo(gbv.w), bf_hi(gbv.w)};
;             float y[8]; float ss = 0.f;
; #pragma unroll
;             for (int e = 0; e < 8; ++e) { y[e] = gbf[e] * (w0[e] * u0[e] + w1[e] * u1[e] + w2[e] * u2[e] + bc[e]); ss += y[e] * y[e]; }
;             const float rstd = 1.0f / sqrtf(wave_sum(ss) * (1.0f / 512.0f) + EPS);
.LBB0_549:
	v_add_co_u32_e32 v70, vcc, s41, v74
	global_load_dwordx4 v[62:65], v[74:75], off offset:3072
	s_nop 0
	v_addc_co_u32_e32 v71, vcc, 0, v75, vcc
	global_load_dwordx4 v[66:69], v[70:71], off offset:1024
	s_nop 0
	global_load_dwordx4 v[70:73], v[70:71], off nt
	s_waitcnt vmcnt(32)
	v_add_co_u32_e32 v86, vcc, s47, v74
	s_movk_i32 s4, 0x4000
	s_nop 0
	v_addc_co_u32_e32 v87, vcc, 0, v75, vcc
	v_add_co_u32_e32 v76, vcc, s39, v74
	s_waitcnt vmcnt(4)
	v_lshlrev_b32_e32 v88, 16, v53
	v_addc_co_u32_e32 v77, vcc, 0, v75, vcc
	v_add_co_u32_e32 v78, vcc, s4, v74
	s_movk_i32 s4, 0x5000
	s_nop 0
	v_addc_co_u32_e32 v79, vcc, 0, v75, vcc
	v_add_co_u32_e32 v80, vcc, s4, v74
	v_and_b32_e32 v89, 0xffff0000, v53
	s_nop 0
	v_addc_co_u32_e32 v81, vcc, 0, v75, vcc
	global_load_dwordx4 v[114:117], v[86:87], off offset:1024
	global_load_dwordx4 v[98:101], v[78:79], off offset:1024
	global_load_dwordx4 v[82:85], v[80:81], off offset:1024
	global_load_dwordx4 v[118:121], v[86:87], off offset:3072
	global_load_dwordx4 v[110:113], v[86:87], off offset:2048 nt
	s_waitcnt vmcnt(8)
	v_lshlrev_b32_e32 v94, 16, v57
	v_and_b32_e32 v95, 0xffff0000, v57
	v_lshlrev_b32_e32 v96, 16, v49
	v_and_b32_e32 v97, 0xffff0000, v49
	v_lshlrev_b32_e32 v102, 16, v61
	v_and_b32_e32 v103, 0xffff0000, v61
	v_lshlrev_b32_e32 v104, 16, v52
	v_and_b32_e32 v105, 0xffff0000, v52
	v_lshlrev_b32_e32 v52, 16, v56
	v_and_b32_e32 v53, 0xffff0000, v56
	v_lshlrev_b32_e32 v56, 16, v48
	v_and_b32_e32 v57, 0xffff0000, v48
	v_lshlrev_b32_e32 v48, 16, v60
	v_and_b32_e32 v49, 0xffff0000, v60
	v_lshlrev_b32_e32 v60, 16, v51
	v_and_b32_e32 v61, 0xffff0000, v51
	v_lshlrev_b32_e32 v106, 16, v55
	v_and_b32_e32 v107, 0xffff0000, v55
	v_pk_mul_f32 v[146:147], v[96:97], v[102:103]
	v_pk_mul_f32 v[144:145], v[56:57], v[48:49]
	v_pk_mul_f32 v[86:87], v[88:89], v[94:95]
	v_pk_mul_f32 v[52:53], v[104:105], v[52:53]
	v_pk_mul_f32 v[48:49], v[60:61], v[106:107]
	v_pk_mul_f32 v[56:57], v[36:37], v[146:147]
	v_pk_mul_f32 v[60:61], v[34:35], v[144:145]
	v_pk_fma_f32 v[56:57], v[32:33], v[86:87], v[56:57]
	v_pk_fma_f32 v[52:53], v[30:31], v[52:53], v[60:61]
	v_and_b32_e32 v51, 0xffff0000, v54
	v_and_b32_e32 v55, 0xffff0000, v46
	s_movk_i32 s4, 0x6000
	v_add_co_u32_e32 v90, vcc, s4, v74
	s_movk_i32 s4, 0x7000
	s_nop 0
	v_addc_co_u32_e32 v91, vcc, 0, v75, vcc
	v_add_co_u32_e32 v92, vcc, s4, v74
	s_mov_b32 s4, 0x8000
	s_nop 0
	v_addc_co_u32_e32 v93, vcc, 0, v75, vcc
	s_waitcnt vmcnt(7)
	v_lshlrev_b32_e32 v60, 16, v65
	v_and_b32_e32 v61, 0xffff0000, v65
	v_lshlrev_b32_e32 v86, 16, v64
	v_and_b32_e32 v87, 0xffff0000, v64
	s_waitcnt vmcnt(6)
	v_lshlrev_b32_e32 v64, 16, v69
	v_and_b32_e32 v65, 0xffff0000, v69
	v_pk_mul_f32 v[132:133], v[60:61], v[64:65]
	v_lshlrev_b32_e32 v60, 16, v47
	v_and_b32_e32 v61, 0xffff0000, v47
	v_lshlrev_b32_e32 v64, 16, v59
	v_and_b32_e32 v65, 0xffff0000, v59
	v_pk_mul_f32 v[148:149], v[60:61], v[64:65]
	v_lshlrev_b32_e32 v60, 16, v63
	v_and_b32_e32 v61, 0xffff0000, v63
	v_lshlrev_b32_e32 v64, 16, v67
	v_and_b32_e32 v65, 0xffff0000, v67
	v_pk_mul_f32 v[134:135], v[60:61], v[64:65]
	v_pk_mul_f32 v[64:65], v[20:21], v[148:149]
	s_waitcnt vmcnt(5)
	v_lshlrev_b32_e32 v60, 16, v71
	v_pk_fma_f32 v[48:49], v[16:17], v[48:49], v[64:65]
	v_and_b32_e32 v61, 0xffff0000, v71
	v_pk_fma_f32 v[48:49], v[24:25], v[134:135], v[48:49]
	v_and_b32_e32 v47, 0xffff0000, v58
	v_pk_add_f32 v[48:49], v[28:29], v[48:49]
	v_lshlrev_b32_e32 v94, 16, v68
	v_pk_mul_f32 v[150:151], v[48:49], v[60:61]
	v_lshlrev_b32_e32 v60, 16, v50
	v_and_b32_e32 v61, 0xffff0000, v50
	v_lshlrev_b32_e32 v50, 16, v54
	v_lshlrev_b32_e32 v54, 16, v46
	v_lshlrev_b32_e32 v46, 16, v58
	v_pk_mul_f32 v[152:153], v[54:55], v[46:47]
	v_lshlrev_b32_e32 v46, 16, v62
	v_and_b32_e32 v47, 0xffff0000, v62
	v_lshlrev_b32_e32 v54, 16, v66
	v_and_b32_e32 v55, 0xffff0000, v66
	v_pk_mul_f32 v[50:51], v[60:61], v[50:51]
	v_pk_mul_f32 v[140:141], v[46:47], v[54:55]
	v_pk_mul_f32 v[54:55], v[18:19], v[152:153]
	v_and_b32_e32 v95, 0xffff0000, v68
	v_pk_fma_f32 v[50:51], v[14:15], v[50:51], v[54:55]
	v_lshlrev_b32_e32 v46, 16, v70
	v_pk_fma_f32 v[50:51], v[22:23], v[140:141], v[50:51]
	v_and_b32_e32 v47, 0xffff0000, v70
	v_pk_add_f32 v[50:51], v[26:27], v[50:51]
	v_pk_mul_f32 v[130:131], v[86:87], v[94:95]
	v_pk_mul_f32 v[154:155], v[50:51], v[46:47]
	v_pk_fma_f32 v[52:53], v[38:39], v[130:131], v[52:53]
	v_pk_mul_f32 v[46:47], v[154:155], v[154:155]
	v_lshlrev_b32_e32 v68, 16, v72
	v_and_b32_e32 v69, 0xffff0000, v72
	v_pk_fma_f32 v[56:57], v[40:41], v[132:133], v[56:57]
	v_pk_add_f32 v[52:53], v[42:43], v[52:53]
	v_pk_mul_f32 v[48:49], v[150:151], v[150:151]
	v_add_f32_e32 v0, v46, v47
	v_lshlrev_b32_e32 v88, 16, v73
	v_and_b32_e32 v89, 0xffff0000, v73
	v_pk_add_f32 v[56:57], v[44:45], v[56:57]
	v_pk_mul_f32 v[138:139], v[52:53], v[68:69]
	v_add_f32_e32 v0, v48, v0
	v_pk_mul_f32 v[136:137], v[56:57], v[88:89]
	v_pk_mul_f32 v[56:57], v[138:139], v[138:139]
	v_add_f32_e32 v0, v49, v0
	v_add_f32_e32 v0, v56, v0
	v_pk_mul_f32 v[52:53], v[136:137], v[136:137]
	v_add_f32_e32 v0, v57, v0
	v_add_f32_e32 v0, v52, v0
	v_add_f32_e32 v0, v53, v0
	v_add_co_u32_e32 v50, vcc, s4, v74
	s_mov_b32 s4, 0x9000
	s_nop 0
	v_addc_co_u32_e32 v51, vcc, 0, v75, vcc
	s_waitcnt lgkmcnt(0)
	s_nop 1
	v_add_f32_dpp v0, v0, v0 quad_perm:[1,0,3,2] row_mask:0xf bank_mask:0xf
	v_add_co_u32_e32 v52, vcc, s4, v74
	s_mov_b32 s4, 0xa000
	s_nop 0
	v_addc_co_u32_e32 v53, vcc, 0, v75, vcc
	s_waitcnt lgkmcnt(0)
	s_nop 1
	v_add_f32_dpp v0, v0, v0 quad_perm:[2,3,0,1] row_mask:0xf bank_mask:0xf
	v_add_co_u32_e32 v54, vcc, s4, v74
	s_mov_b32 s4, 0xb000
	s_nop 0
	v_addc_co_u32_e32 v55, vcc, 0, v75, vcc
	s_waitcnt lgkmcnt(0)
; __device__ __forceinline__ unsigned cvtpk(float lo, float hi) { f32x2 v = {lo, hi}; bf16x2_t b = __builtin_convertvector(v, bf16x2_t); return __builtin_bit_cast(unsigned, b); }
; #define GAS __attribute__((address_space(1)))
; __device__ __forceinline__ float bf_lo(unsigned w) { return __uint_as_float(w << 16); }
; __device__ __forceinline__ float bf_hi(unsigned w) { return __uint_as_float(w & 0xffff0000u); }
; #define CV_U(dst, xv, gv) do { dst[0] = bf_lo(xv.x) * bf_lo(gv.x); dst[1] = bf_hi(xv.x) * bf_hi(gv.x); dst[2] = bf_lo(xv.y) * bf_lo(gv.y); dst[3] = bf_hi(xv.y) * bf_hi(gv.y); \
;         dst[4] = bf_lo(xv.z) * bf_lo(gv.z); dst[5] = bf_hi(xv.z) * bf_hi(gv.z); dst[6] = bf_lo(xv.w) * bf_lo(gv.w); dst[7] = bf_hi(xv.w) * bf_hi(gv.w); } while (0)
; __device__ __forceinline__ void conv_unit(const bf16* PROJ, bf16* YMIX, const float* w_conv, const float* b_conv, const float* g_conv, int b, int c, int wave, int lane_in) {
;     ...
;         for (int r = 0; r < 8; ++r) {
;             float u2[8]; CV_U(u2, xa[r + 2], ga[r + 2]);
;             const u32x4 gbv = gb[r];
;             float gbf[8] = {bf_lo(gbv.x), bf_hi(gbv.x), bf_lo(gbv.y), bf_hi(gbv.y), bf_lo(gbv.z), bf_hi(gbv.z), bf_lo(gbv.w), bf_hi(gbv.w)};
;             float y[8]; float ss = 0.f;
; #pragma unroll
;             for (int e = 0; e < 8; ++e) { y[e] = gbf[e] * (w0[e] * u0[e] + w1[e] * u1[e] + w2[e] * u2[e] + bc[e]); ss += y[e] * y[e]; }
;             const float rstd = 1.0f / sqrtf(wave_sum(ss) * (1.0f / 512.0f) + EPS);
;             u32x4 o;
;             o.x = cvtpk(y[0] * rstd * gc[0], y[1] * rstd * gc[1]); o.y = cvtpk(y[2] * rstd * gc[2], y[3] * rstd * gc[3]);
;             o.z = cvtpk(y[4] * rstd * gc[4], y[5] * rstd * gc[5]); o.w = cvtpk(y[6] * rstd * gc[6], y[7] * rstd * gc[7]);
;             *(GAS u32x4*)(YMIX + ((size_t)b * SEQ + s0 + r) * D + 512 + ch0) = o;
	s_nop 1
	v_add_f32_dpp v0, v0, v0 row_half_mirror row_mask:0xf bank_mask:0xf
	v_add_co_u32_e32 v142, vcc, s4, v74
	global_load_dwordx4 v[86:89], v[92:93], off offset:1024
	global_load_dwordx4 v[70:73], v[50:51], off offset:1024
	v_addc_co_u32_e32 v143, vcc, 0, v75, vcc
	s_waitcnt lgkmcnt(0)
	s_nop 1
	v_add_f32_dpp v0, v0, v0 row_mirror row_mask:0xf bank_mask:0xf
	global_load_dwordx4 v[58:61], v[54:55], off offset:1024
	global_load_dwordx4 v[46:49], v[142:143], off offset:1024
	global_load_dwordx4 v[126:129], v[76:77], off offset:3072
	global_load_dwordx4 v[122:125], v[78:79], off nt
	global_load_dwordx4 v[106:109], v[80:81], off offset:3072
	global_load_dwordx4 v[102:105], v[80:81], off offset:2048 nt
	global_load_dwordx4 v[94:97], v[90:91], off offset:3072
	s_nop 0
	global_load_dwordx4 v[90:93], v[92:93], off nt
	s_nop 0
	global_load_dwordx4 v[78:81], v[50:51], off offset:3072
	global_load_dwordx4 v[74:77], v[50:51], off offset:2048 nt
	global_load_dwordx4 v[66:69], v[52:53], off offset:3072
	global_load_dwordx4 v[62:65], v[54:55], off nt
	s_nop 0
	global_load_dwordx4 v[54:57], v[142:143], off offset:3072
	global_load_dwordx4 v[50:53], v[142:143], off offset:2048 nt
	s_waitcnt lgkmcnt(0)
	v_mov_b32_e32 v5, v0
	v_mov_b32_e32 v253, v0
	s_nop 1
	v_permlane16_swap_b32_e32 v5, v253
	v_add_f32_e32 v0, v5, v253
	s_waitcnt vmcnt(17)
	v_lshlrev_b32_e32 v156, 16, v121
	v_and_b32_e32 v157, 0xffff0000, v121
	v_pk_mul_f32 v[158:159], v[36:37], v[132:133]
	s_waitcnt vmcnt(16)
	v_and_b32_e32 v121, 0xffff0000, v112
	s_waitcnt lgkmcnt(0)
	v_mov_b32_e32 v5, v0
	v_mov_b32_e32 v253, v0
	s_nop 1
	v_permlane32_swap_b32_e32 v5, v253
	v_add_f32_e32 v0, v5, v253
	v_fmamk_f32 v0, v0, 0x3b000000, v220
	v_mul_f32_e32 v5, 0x4f800000, v0
	v_cmp_gt_f32_e32 vcc, s45, v0
	v_pk_fma_f32 v[146:147], v[32:33], v[146:147], v[158:159]
	v_lshlrev_b32_e32 v158, 16, v116
	v_cndmask_b32_e32 v0, v0, v5, vcc
	v_sqrt_f32_e32 v5, v0
	v_and_b32_e32 v159, 0xffff0000, v116
	v_lshlrev_b32_e32 v116, 16, v120
	v_pk_mul_f32 v[160:161], v[20:21], v[134:135]
	v_add_u32_e32 v142, -1, v5
	v_fma_f32 v143, -v142, v5, v0
	v_cmp_ge_f32_e64 s[4:5], 0, v143
	v_add_u32_e32 v143, 1, v5
	v_pk_fma_f32 v[148:149], v[16:17], v[148:149], v[160:161]
	v_cndmask_b32_e64 v142, v5, v142, s[4:5]
	v_fma_f32 v5, -v143, v5, v0
	v_cmp_lt_f32_e64 s[4:5], 0, v5
	v_lshlrev_b32_e32 v160, 16, v114
	v_and_b32_e32 v161, 0xffff0000, v114
	v_cndmask_b32_e64 v5, v142, v143, s[4:5]
	v_mul_f32_e32 v142, 0x37800000, v5
	v_cndmask_b32_e32 v5, v5, v142, vcc
	v_lshlrev_b32_e32 v142, 16, v117
	v_and_b32_e32 v143, 0xffff0000, v117
	v_pk_mul_f32 v[142:143], v[142:143], v[156:157]
	v_lshlrev_b32_e32 v156, 16, v113
	v_and_b32_e32 v157, 0xffff0000, v113
	v_and_b32_e32 v117, 0xffff0000, v120
	v_lshlrev_b32_e32 v120, 16, v112
	v_pk_mul_f32 v[112:113], v[34:35], v[130:131]
	v_pk_mul_f32 v[116:117], v[158:159], v[116:117]
	v_pk_fma_f32 v[112:113], v[30:31], v[144:145], v[112:113]
	v_lshlrev_b32_e32 v158, 16, v119
	v_pk_fma_f32 v[112:113], v[38:39], v[116:117], v[112:113]
	v_and_b32_e32 v159, 0xffff0000, v119
	v_pk_add_f32 v[112:113], v[42:43], v[112:113]
	v_lshlrev_b32_e32 v114, 16, v118
	v_pk_mul_f32 v[144:145], v[112:113], v[120:121]
	v_lshlrev_b32_e32 v112, 16, v115
	v_and_b32_e32 v113, 0xffff0000, v115
	v_pk_mul_f32 v[112:113], v[112:113], v[158:159]
	v_lshlrev_b32_e32 v158, 16, v111
	v_and_b32_e32 v159, 0xffff0000, v111
	v_and_b32_e32 v115, 0xffff0000, v118
	v_lshlrev_b32_e32 v118, 16, v110
	v_and_b32_e32 v119, 0xffff0000, v110
	v_pk_mul_f32 v[110:111], v[18:19], v[140:141]
	v_pk_mul_f32 v[114:115], v[160:161], v[114:115]
	v_pk_fma_f32 v[110:111], v[14:15], v[152:153], v[110:111]
	v_pk_fma_f32 v[148:149], v[24:25], v[112:113], v[148:149]
	v_pk_fma_f32 v[110:111], v[22:23], v[114:115], v[110:111]
	v_pk_add_f32 v[148:149], v[28:29], v[148:149]
	v_pk_add_f32 v[110:111], v[26:27], v[110:111]
	v_pk_mul_f32 v[158:159], v[148:149], v[158:159]
	v_pk_mul_f32 v[152:153], v[110:111], v[118:119]
	v_pk_mul_f32 v[148:149], v[158:159], v[158:159]
	v_pk_mul_f32 v[110:111], v[152:153], v[152:153]
	v_pk_fma_f32 v[146:147], v[40:41], v[142:143], v[146:147]
	v_add_f32_e32 v110, v110, v111
	v_add_f32_e32 v110, v148, v110
	v_pk_add_f32 v[146:147], v[44:45], v[146:147]
	v_pk_mul_f32 v[120:121], v[144:145], v[144:145]
	v_add_f32_e32 v110, v149, v110
	v_pk_mul_f32 v[146:147], v[146:147], v[156:157]
	v_add_f32_e32 v110, v120, v110
	v_pk_mul_f32 v[156:157], v[146:147], v[146:147]
	v_add_f32_e32 v110, v121, v110
	v_add_f32_e32 v110, v156, v110
	v_cmp_class_f32_e32 vcc, v0, v221
	v_add_f32_e32 v110, v157, v110
	v_cndmask_b32_e32 v0, v5, v0, vcc
	v_div_scale_f32 v5, s[4:5], v0, v0, 1.0
	v_rcp_f32_e32 v162, v5
	s_waitcnt lgkmcnt(0)
	s_nop 1
	v_add_f32_dpp v110, v110, v110 quad_perm:[1,0,3,2] row_mask:0xf bank_mask:0xf
	s_lshl_b64 s[4:5], s[6:7], 11
	v_fma_f32 v118, -v5, v162, 1.0
	v_fmac_f32_e32 v162, v118, v162
	v_div_scale_f32 v118, vcc, 1.0, v0, 1.0
	v_mul_f32_e32 v119, v118, v162
	v_fma_f32 v120, -v5, v119, v118
	v_fmac_f32_e32 v119, v120, v162
	v_fma_f32 v5, -v5, v119, v118
	s_waitcnt lgkmcnt(0)
	s_nop 1
	v_add_f32_dpp v118, v110, v110 quad_perm:[2,3,0,1] row_mask:0xf bank_mask:0xf
	v_div_fmas_f32 v5, v5, v162, v119
	v_div_fixup_f32 v0, v5, v0, 1.0
	v_pk_mul_f32 v[110:111], v[154:155], v[0:1] op_sel_hi:[1,0]
	s_add_u32 s4, s79, s4
	s_waitcnt lgkmcnt(0)
	s_nop 1
	v_add_f32_dpp v5, v118, v118 row_half_mirror row_mask:0xf bank_mask:0xf
	v_pk_mul_f32 v[110:111], v[10:11], v[110:111]
	s_addc_u32 s5, s80, s5
	v_cvt_pk_bf16_f32 v148, v110, v111
	v_pk_mul_f32 v[110:111], v[150:151], v[0:1] op_sel_hi:[1,0]
	s_waitcnt lgkmcnt(0)
; __device__ __forceinline__ unsigned cvtpk(float lo, float hi) { f32x2 v = {lo, hi}; bf16x2_t b = __builtin_convertvector(v, bf16x2_t); return __builtin_bit_cast(unsigned, b); }
; #define GAS __attribute__((address_space(1)))
; __device__ __forceinline__ float bf_lo(unsigned w) { return __uint_as_float(w << 16); }
; __device__ __forceinline__ float bf_hi(unsigned w) { return __uint_as_float(w & 0xffff0000u); }
; #define CV_U(dst, xv, gv) do { dst[0] = bf_lo(xv.x) * bf_lo(gv.x); dst[1] = bf_hi(xv.x) * bf_hi(gv.x); dst[2] = bf_lo(xv.y) * bf_lo(gv.y); dst[3] = bf_hi(xv.y) * bf_hi(gv.y); \
;         dst[4] = bf_lo(xv.z) * bf_lo(gv.z); dst[5] = bf_hi(xv.z) * bf_hi(gv.z); dst[6] = bf_lo(xv.w) * bf_lo(gv.w); dst[7] = bf_hi(xv.w) * bf_hi(gv.w); } while (0)
; __device__ __forceinline__ void conv_unit(const bf16* PROJ, bf16* YMIX, const float* w_conv, const float* b_conv, const float* g_conv, int b, int c, int wave, int lane_in) {
;     ...
;         for (int r = 0; r < 8; ++r) {
;             float u2[8]; CV_U(u2, xa[r + 2], ga[r + 2]);
;             const u32x4 gbv = gb[r];
;             float gbf[8] = {bf_lo(gbv.x), bf_hi(gbv.x), bf_lo(gbv.y), bf_hi(gbv.y), bf_lo(gbv.z), bf_hi(gbv.z), bf_lo(gbv.w), bf_hi(gbv.w)};
;             float y[8]; float ss = 0.f;
; #pragma unroll
;             for (int e = 0; e < 8; ++e) { y[e] = gbf[e] * (w0[e] * u0[e] + w1[e] * u1[e] + w2[e] * u2[e] + bc[e]); ss += y[e] * y[e]; }
;             const float rstd = 1.0f / sqrtf(wave_sum(ss) * (1.0f / 512.0f) + EPS);
;             u32x4 o;
;             o.x = cvtpk(y[0] * rstd * gc[0], y[1] * rstd * gc[1]); o.y = cvtpk(y[2] * rstd * gc[2], y[3] * rstd * gc[3]);
;             o.z = cvtpk(y[4] * rstd * gc[4], y[5] * rstd * gc[5]); o.w = cvtpk(y[6] * rstd * gc[6], y[7] * rstd * gc[7]);
;             *(GAS u32x4*)(YMIX + ((size_t)b * SEQ + s0 + r) * D + 512 + ch0) = o;
	s_nop 1
	v_add_f32_dpp v5, v5, v5 row_mirror row_mask:0xf bank_mask:0xf
	v_pk_mul_f32 v[110:111], v[12:13], v[110:111]
	v_lshl_add_u64 v[2:3], v[2:3], 1, s[4:5]
	v_cvt_pk_bf16_f32 v149, v110, v111
	v_pk_mul_f32 v[110:111], v[138:139], v[0:1] op_sel_hi:[1,0]
	s_waitcnt lgkmcnt(0)
	v_mov_b32_e32 v118, v5
	v_mov_b32_e32 v253, v5
	s_nop 1
	v_permlane16_swap_b32_e32 v118, v253
	v_add_f32_e32 v5, v118, v253
	v_pk_mul_f32 v[110:111], v[6:7], v[110:111]
	v_and_b32_e32 v119, 0xffff0000, v101
	v_cvt_pk_bf16_f32 v150, v110, v111
	v_pk_mul_f32 v[110:111], v[136:137], v[0:1] op_sel_hi:[1,0]
	s_waitcnt lgkmcnt(0)
	v_mov_b32_e32 v118, v5
	v_mov_b32_e32 v253, v5
	s_nop 1
	v_permlane32_swap_b32_e32 v118, v253
	v_add_f32_e32 v0, v118, v253
	v_fmamk_f32 v0, v0, 0x3b000000, v220
	v_mul_f32_e32 v5, 0x4f800000, v0
	v_cmp_gt_f32_e32 vcc, s45, v0
	v_pk_mul_f32 v[110:111], v[8:9], v[110:111]
	v_lshlrev_b32_e32 v118, 16, v101
	v_cndmask_b32_e32 v0, v0, v5, vcc
	v_sqrt_f32_e32 v5, v0
	v_cvt_pk_bf16_f32 v151, v110, v111
	v_pk_mul_f32 v[120:121], v[36:37], v[142:143]
	s_waitcnt vmcnt(10)
	v_and_b32_e32 v101, 0xffff0000, v124
	v_add_u32_e32 v110, -1, v5
	v_fma_f32 v111, -v110, v5, v0
	v_cmp_ge_f32_e64 s[4:5], 0, v111
	v_add_u32_e32 v111, 1, v5
	v_pk_fma_f32 v[120:121], v[32:33], v[132:133], v[120:121]
	v_cndmask_b32_e64 v110, v5, v110, s[4:5]
	v_fma_f32 v5, -v111, v5, v0
	v_cmp_lt_f32_e64 s[4:5], 0, v5
	global_store_dwordx4 v[2:3], v[148:151], off offset:1024
	s_add_i32 s9, s9, 64
	v_cndmask_b32_e64 v5, v110, v111, s[4:5]
	v_mul_f32_e32 v110, 0x37800000, v5
	v_cndmask_b32_e32 v5, v5, v110, vcc
	v_lshlrev_b32_e32 v110, 16, v129
	v_and_b32_e32 v111, 0xffff0000, v129
	v_pk_mul_f32 v[110:111], v[110:111], v[118:119]
	v_lshlrev_b32_e32 v118, 16, v125
	v_pk_fma_f32 v[120:121], v[40:41], v[110:111], v[120:121]
	v_and_b32_e32 v119, 0xffff0000, v125
	v_pk_add_f32 v[120:121], v[44:45], v[120:121]
	v_and_b32_e32 v125, 0xffff0000, v99
	v_pk_mul_f32 v[132:133], v[120:121], v[118:119]
	v_lshlrev_b32_e32 v118, 16, v128
	v_and_b32_e32 v119, 0xffff0000, v128
	v_lshlrev_b32_e32 v120, 16, v100
	v_and_b32_e32 v121, 0xffff0000, v100
	v_pk_mul_f32 v[118:119], v[118:119], v[120:121]
	v_pk_mul_f32 v[120:121], v[34:35], v[116:117]
	v_lshlrev_b32_e32 v100, 16, v124
	v_pk_fma_f32 v[120:121], v[30:31], v[130:131], v[120:121]
	v_lshlrev_b32_e32 v124, 16, v99
	v_pk_fma_f32 v[120:121], v[38:39], v[118:119], v[120:121]
	v_pk_mul_f32 v[128:129], v[20:21], v[112:113]
	v_pk_add_f32 v[120:121], v[42:43], v[120:121]
	v_pk_fma_f32 v[128:129], v[16:17], v[134:135], v[128:129]
	v_pk_mul_f32 v[130:131], v[120:121], v[100:101]
	v_lshlrev_b32_e32 v120, 16, v127
	v_and_b32_e32 v121, 0xffff0000, v127
	v_pk_mul_f32 v[120:121], v[120:121], v[124:125]
	v_lshlrev_b32_e32 v124, 16, v123
	v_pk_fma_f32 v[128:129], v[24:25], v[120:121], v[128:129]
	v_and_b32_e32 v125, 0xffff0000, v123
	v_pk_add_f32 v[128:129], v[28:29], v[128:129]
	v_and_b32_e32 v127, 0xffff0000, v98
	v_pk_mul_f32 v[134:135], v[128:129], v[124:125]
	v_lshlrev_b32_e32 v124, 16, v126
	v_and_b32_e32 v125, 0xffff0000, v126
	v_lshlrev_b32_e32 v126, 16, v98
	v_lshlrev_b32_e32 v98, 16, v122
	v_and_b32_e32 v99, 0xffff0000, v122
	v_pk_mul_f32 v[122:123], v[18:19], v[114:115]
	v_pk_mul_f32 v[124:125], v[124:125], v[126:127]
	v_pk_fma_f32 v[122:123], v[14:15], v[140:141], v[122:123]
	v_cmp_class_f32_e32 vcc, v0, v221
	v_pk_fma_f32 v[122:123], v[22:23], v[124:125], v[122:123]
	v_pk_mul_f32 v[128:129], v[134:135], v[134:135]
	v_pk_add_f32 v[122:123], v[26:27], v[122:123]
	v_cndmask_b32_e32 v0, v5, v0, vcc
	v_pk_mul_f32 v[138:139], v[122:123], v[98:99]
	v_pk_mul_f32 v[100:101], v[130:131], v[130:131]
	v_pk_mul_f32 v[98:99], v[138:139], v[138:139]
	v_pk_mul_f32 v[136:137], v[132:133], v[132:133]
	v_add_f32_e32 v5, v98, v99
	v_add_f32_e32 v5, v128, v5
	v_add_f32_e32 v5, v129, v5
	v_add_f32_e32 v5, v100, v5
	v_add_f32_e32 v5, v101, v5
	v_add_f32_e32 v5, v136, v5
	v_add_f32_e32 v5, v137, v5
	v_div_scale_f32 v99, s[4:5], v0, v0, 1.0
	v_rcp_f32_e32 v100, v99
	v_pk_mul_f32 v[140:141], v[20:21], v[120:121]
	s_waitcnt lgkmcnt(0)
	s_nop 1
	v_add_f32_dpp v5, v5, v5 quad_perm:[1,0,3,2] row_mask:0xf bank_mask:0xf
	v_fma_f32 v101, -v99, v100, 1.0
	v_fmac_f32_e32 v100, v101, v100
	v_div_scale_f32 v101, vcc, 1.0, v0, 1.0
	s_waitcnt lgkmcnt(0)
	s_nop 1
	v_add_f32_dpp v5, v5, v5 quad_perm:[2,3,0,1] row_mask:0xf bank_mask:0xf
	v_mul_f32_e32 v122, v101, v100
	v_fma_f32 v123, -v99, v122, v101
	v_fmac_f32_e32 v122, v123, v100
	v_fma_f32 v99, -v99, v122, v101
	s_waitcnt lgkmcnt(0)
	s_nop 1
	v_add_f32_dpp v5, v5, v5 row_half_mirror row_mask:0xf bank_mask:0xf
	v_div_fmas_f32 v98, v99, v100, v122
	v_div_fixup_f32 v0, v98, v0, 1.0
	v_pk_mul_f32 v[98:99], v[152:153], v[0:1] op_sel_hi:[1,0]
	v_pk_mul_f32 v[122:123], v[36:37], v[110:111]
	s_waitcnt lgkmcnt(0)
	s_nop 1
	v_add_f32_dpp v5, v5, v5 row_mirror row_mask:0xf bank_mask:0xf
	v_pk_mul_f32 v[98:99], v[10:11], v[98:99]
	s_waitcnt vmcnt(10)
	v_and_b32_e32 v101, 0xffff0000, v109
	v_cvt_pk_bf16_f32 v126, v98, v99
	v_pk_mul_f32 v[98:99], v[158:159], v[0:1] op_sel_hi:[1,0]
	s_waitcnt lgkmcnt(0)
	v_mov_b32_e32 v100, v5
	v_mov_b32_e32 v253, v5
	s_nop 1
	v_permlane16_swap_b32_e32 v100, v253
	v_add_f32_e32 v5, v100, v253
	v_pk_mul_f32 v[98:99], v[12:13], v[98:99]
	v_pk_fma_f32 v[122:123], v[32:33], v[142:143], v[122:123]
	v_cvt_pk_bf16_f32 v127, v98, v99
	v_pk_mul_f32 v[98:99], v[144:145], v[0:1] op_sel_hi:[1,0]
	s_waitcnt lgkmcnt(0)
; __device__ __forceinline__ unsigned cvtpk(float lo, float hi) { f32x2 v = {lo, hi}; bf16x2_t b = __builtin_convertvector(v, bf16x2_t); return __builtin_bit_cast(unsigned, b); }
; #define GAS __attribute__((address_space(1)))
; __device__ __forceinline__ float bf_lo(unsigned w) { return __uint_as_float(w << 16); }
; __device__ __forceinline__ float bf_hi(unsigned w) { return __uint_as_float(w & 0xffff0000u); }
; #define CV_U(dst, xv, gv) do { dst[0] = bf_lo(xv.x) * bf_lo(gv.x); dst[1] = bf_hi(xv.x) * bf_hi(gv.x); dst[2] = bf_lo(xv.y) * bf_lo(gv.y); dst[3] = bf_hi(xv.y) * bf_hi(gv.y); \
;         dst[4] = bf_lo(xv.z) * bf_lo(gv.z); dst[5] = bf_hi(xv.z) * bf_hi(gv.z); dst[6] = bf_lo(xv.w) * bf_lo(gv.w); dst[7] = bf_hi(xv.w) * bf_hi(gv.w); } while (0)
; __device__ __forceinline__ void conv_unit(const bf16* PROJ, bf16* YMIX, const float* w_conv, const float* b_conv, const float* g_conv, int b, int c, int wave, int lane_in) {
;     ...
;         for (int r = 0; r < 8; ++r) {
;             float u2[8]; CV_U(u2, xa[r + 2], ga[r + 2]);
;             const u32x4 gbv = gb[r];
;             float gbf[8] = {bf_lo(gbv.x), bf_hi(gbv.x), bf_lo(gbv.y), bf_hi(gbv.y), bf_lo(gbv.z), bf_hi(gbv.z), bf_lo(gbv.w), bf_hi(gbv.w)};
;             float y[8]; float ss = 0.f;
; #pragma unroll
;             for (int e = 0; e < 8; ++e) { y[e] = gbf[e] * (w0[e] * u0[e] + w1[e] * u1[e] + w2[e] * u2[e] + bc[e]); ss += y[e] * y[e]; }
;             const float rstd = 1.0f / sqrtf(wave_sum(ss) * (1.0f / 512.0f) + EPS);
;             u32x4 o;
;             o.x = cvtpk(y[0] * rstd * gc[0], y[1] * rstd * gc[1]); o.y = cvtpk(y[2] * rstd * gc[2], y[3] * rstd * gc[3]);
;             o.z = cvtpk(y[4] * rstd * gc[4], y[5] * rstd * gc[5]); o.w = cvtpk(y[6] * rstd * gc[6], y[7] * rstd * gc[7]);
;             *(GAS u32x4*)(YMIX + ((size_t)b * SEQ + s0 + r) * D + 512 + ch0) = o;
	v_mov_b32_e32 v100, v5
	v_mov_b32_e32 v253, v5
	s_nop 1
	v_permlane32_swap_b32_e32 v100, v253
	v_add_f32_e32 v5, v100, v253
	v_pk_mul_f32 v[98:99], v[6:7], v[98:99]
	v_fmamk_f32 v5, v5, 0x3b000000, v220
	v_cvt_pk_bf16_f32 v128, v98, v99
	v_mul_f32_e32 v98, 0x4f800000, v5
	v_cmp_gt_f32_e32 vcc, s45, v5
	v_pk_fma_f32 v[112:113], v[16:17], v[112:113], v[140:141]
	v_lshlrev_b32_e32 v140, 16, v82
	v_cndmask_b32_e32 v5, v5, v98, vcc
	v_sqrt_f32_e32 v100, v5
	v_pk_mul_f32 v[98:99], v[146:147], v[0:1] op_sel_hi:[1,0]
	v_and_b32_e32 v141, 0xffff0000, v82
	v_pk_mul_f32 v[98:99], v[8:9], v[98:99]
	v_add_u32_e32 v0, -1, v100
	v_cvt_pk_bf16_f32 v129, v98, v99
	v_fma_f32 v98, -v0, v100, v5
	v_cmp_ge_f32_e64 s[4:5], 0, v98
	v_add_u32_e32 v98, 1, v100
	v_fma_f32 v99, -v98, v100, v5
	v_cndmask_b32_e64 v0, v100, v0, s[4:5]
	v_cmp_lt_f32_e64 s[4:5], 0, v99
	v_and_b32_e32 v99, 0xffff0000, v85
	v_lshlrev_b32_e32 v100, 16, v109
	v_cndmask_b32_e64 v0, v0, v98, s[4:5]
	v_mul_f32_e32 v98, 0x37800000, v0
	v_cndmask_b32_e32 v0, v0, v98, vcc
	v_lshlrev_b32_e32 v98, 16, v85
	v_pk_mul_f32 v[98:99], v[98:99], v[100:101]
	s_waitcnt vmcnt(9)
	v_lshlrev_b32_e32 v100, 16, v105
	v_pk_fma_f32 v[122:123], v[40:41], v[98:99], v[122:123]
	v_and_b32_e32 v101, 0xffff0000, v105
	v_pk_add_f32 v[122:123], v[44:45], v[122:123]
	v_and_b32_e32 v85, 0xffff0000, v108
	v_pk_mul_f32 v[122:123], v[122:123], v[100:101]
	v_lshlrev_b32_e32 v100, 16, v84
	v_and_b32_e32 v101, 0xffff0000, v84
	v_lshlrev_b32_e32 v84, 16, v108
	v_pk_mul_f32 v[100:101], v[100:101], v[84:85]
	v_lshlrev_b32_e32 v84, 16, v104
	v_and_b32_e32 v85, 0xffff0000, v104
	v_pk_mul_f32 v[104:105], v[34:35], v[118:119]
	v_lshlrev_b32_e32 v82, 16, v106
	v_pk_fma_f32 v[104:105], v[30:31], v[116:117], v[104:105]
	v_lshlrev_b32_e32 v116, 16, v107
	v_pk_fma_f32 v[104:105], v[38:39], v[100:101], v[104:105]
	v_and_b32_e32 v117, 0xffff0000, v107
	v_pk_add_f32 v[104:105], v[42:43], v[104:105]
	v_cmp_class_f32_e32 vcc, v5, v221
	v_pk_mul_f32 v[108:109], v[104:105], v[84:85]
	v_lshlrev_b32_e32 v104, 16, v83
	v_and_b32_e32 v105, 0xffff0000, v83
	v_and_b32_e32 v83, 0xffff0000, v106
	v_pk_mul_f32 v[104:105], v[104:105], v[116:117]
	v_lshlrev_b32_e32 v116, 16, v103
	v_and_b32_e32 v117, 0xffff0000, v103
	v_pk_mul_f32 v[106:107], v[140:141], v[82:83]
	v_lshlrev_b32_e32 v82, 16, v102
	v_and_b32_e32 v83, 0xffff0000, v102
	v_pk_mul_f32 v[102:103], v[18:19], v[124:125]
	v_pk_fma_f32 v[112:113], v[24:25], v[104:105], v[112:113]
	v_pk_fma_f32 v[102:103], v[14:15], v[114:115], v[102:103]
	v_pk_add_f32 v[112:113], v[28:29], v[112:113]
	v_pk_fma_f32 v[102:103], v[22:23], v[106:107], v[102:103]
	v_pk_mul_f32 v[116:117], v[112:113], v[116:117]
	v_pk_add_f32 v[102:103], v[26:27], v[102:103]
	v_cndmask_b32_e32 v0, v0, v5, vcc
	v_pk_mul_f32 v[140:141], v[102:103], v[82:83]
	v_pk_mul_f32 v[112:113], v[116:117], v[116:117]
	v_pk_mul_f32 v[82:83], v[140:141], v[140:141]
	v_pk_mul_f32 v[84:85], v[108:109], v[108:109]
	v_add_f32_e32 v5, v82, v83
	v_add_f32_e32 v5, v112, v5
	v_add_f32_e32 v5, v113, v5
	v_add_f32_e32 v5, v84, v5
	v_pk_mul_f32 v[136:137], v[122:123], v[122:123]
	v_add_f32_e32 v5, v85, v5
	v_add_f32_e32 v5, v136, v5
	v_add_f32_e32 v5, v137, v5
	v_div_scale_f32 v83, s[4:5], v0, v0, 1.0
	v_rcp_f32_e32 v84, v83
	global_store_dwordx4 v[2:3], v[126:129], off offset:3072
	s_waitcnt lgkmcnt(0)
	s_nop 1
	v_add_f32_dpp v5, v5, v5 quad_perm:[1,0,3,2] row_mask:0xf bank_mask:0xf
	v_fma_f32 v85, -v83, v84, 1.0
	v_fmac_f32_e32 v84, v85, v84
	v_div_scale_f32 v85, vcc, 1.0, v0, 1.0
	s_waitcnt lgkmcnt(0)
	s_nop 1
	v_add_f32_dpp v5, v5, v5 quad_perm:[2,3,0,1] row_mask:0xf bank_mask:0xf
	v_mul_f32_e32 v102, v85, v84
	v_fma_f32 v103, -v83, v102, v85
	v_fmac_f32_e32 v102, v103, v84
	v_fma_f32 v83, -v83, v102, v85
	s_waitcnt lgkmcnt(0)
	s_nop 1
	v_add_f32_dpp v5, v5, v5 row_half_mirror row_mask:0xf bank_mask:0xf
	v_div_fmas_f32 v82, v83, v84, v102
	v_div_fixup_f32 v0, v82, v0, 1.0
	v_pk_mul_f32 v[82:83], v[138:139], v[0:1] op_sel_hi:[1,0]
	v_pk_mul_f32 v[102:103], v[36:37], v[98:99]
	s_waitcnt lgkmcnt(0)
	s_nop 1
	v_add_f32_dpp v5, v5, v5 row_mirror row_mask:0xf bank_mask:0xf
	v_pk_mul_f32 v[82:83], v[10:11], v[82:83]
	v_and_b32_e32 v85, 0xffff0000, v89
	v_cvt_pk_bf16_f32 v112, v82, v83
	v_pk_mul_f32 v[82:83], v[134:135], v[0:1] op_sel_hi:[1,0]
	s_waitcnt lgkmcnt(0)
	v_mov_b32_e32 v84, v5
	v_mov_b32_e32 v253, v5
	s_nop 1
	v_permlane16_swap_b32_e32 v84, v253
	v_add_f32_e32 v5, v84, v253
	v_pk_mul_f32 v[82:83], v[12:13], v[82:83]
	v_pk_fma_f32 v[102:103], v[32:33], v[110:111], v[102:103]
	v_cvt_pk_bf16_f32 v113, v82, v83
	v_pk_mul_f32 v[82:83], v[130:131], v[0:1] op_sel_hi:[1,0]
	s_waitcnt lgkmcnt(0)
	v_mov_b32_e32 v84, v5
	v_mov_b32_e32 v253, v5
	s_nop 1
	v_permlane32_swap_b32_e32 v84, v253
	v_add_f32_e32 v5, v84, v253
	v_pk_mul_f32 v[82:83], v[6:7], v[82:83]
	v_fmamk_f32 v5, v5, 0x3b000000, v220
	v_cvt_pk_bf16_f32 v114, v82, v83
	v_mul_f32_e32 v82, 0x4f800000, v5
	v_cmp_gt_f32_e32 vcc, s45, v5
	v_pk_mul_f32 v[126:127], v[20:21], v[104:105]
	s_nop 0
	v_cndmask_b32_e32 v5, v5, v82, vcc
	v_sqrt_f32_e32 v84, v5
	v_pk_mul_f32 v[82:83], v[132:133], v[0:1] op_sel_hi:[1,0]
	v_pk_fma_f32 v[120:121], v[16:17], v[120:121], v[126:127]
	v_pk_mul_f32 v[82:83], v[8:9], v[82:83]
	v_add_u32_e32 v0, -1, v84
	v_cvt_pk_bf16_f32 v115, v82, v83
	v_fma_f32 v82, -v0, v84, v5
	v_cmp_ge_f32_e64 s[4:5], 0, v82
	v_add_u32_e32 v82, 1, v84
	v_fma_f32 v83, -v82, v84, v5
	v_cndmask_b32_e64 v0, v84, v0, s[4:5]
	v_cmp_lt_f32_e64 s[4:5], 0, v83
	s_waitcnt vmcnt(9)
	v_and_b32_e32 v83, 0xffff0000, v97
	v_lshlrev_b32_e32 v84, 16, v89
	v_cndmask_b32_e64 v0, v0, v82, s[4:5]
	v_mul_f32_e32 v82, 0x37800000, v0
	v_cndmask_b32_e32 v0, v0, v82, vcc
	v_lshlrev_b32_e32 v82, 16, v97
	v_pk_mul_f32 v[82:83], v[82:83], v[84:85]
	s_waitcnt vmcnt(8)
; __device__ __forceinline__ unsigned cvtpk(float lo, float hi) { f32x2 v = {lo, hi}; bf16x2_t b = __builtin_convertvector(v, bf16x2_t); return __builtin_bit_cast(unsigned, b); }
; #define GAS __attribute__((address_space(1)))
; __device__ __forceinline__ float bf_lo(unsigned w) { return __uint_as_float(w << 16); }
; __device__ __forceinline__ float bf_hi(unsigned w) { return __uint_as_float(w & 0xffff0000u); }
; #define CV_U(dst, xv, gv) do { dst[0] = bf_lo(xv.x) * bf_lo(gv.x); dst[1] = bf_hi(xv.x) * bf_hi(gv.x); dst[2] = bf_lo(xv.y) * bf_lo(gv.y); dst[3] = bf_hi(xv.y) * bf_hi(gv.y); \
;         dst[4] = bf_lo(xv.z) * bf_lo(gv.z); dst[5] = bf_hi(xv.z) * bf_hi(gv.z); dst[6] = bf_lo(xv.w) * bf_lo(gv.w); dst[7] = bf_hi(xv.w) * bf_hi(gv.w); } while (0)
; __device__ __forceinline__ void conv_unit(const bf16* PROJ, bf16* YMIX, const float* w_conv, const float* b_conv, const float* g_conv, int b, int c, int wave, int lane_in) {
;     ...
;         for (int r = 0; r < 8; ++r) {
;             float u2[8]; CV_U(u2, xa[r + 2], ga[r + 2]);
;             const u32x4 gbv = gb[r];
;             float gbf[8] = {bf_lo(gbv.x), bf_hi(gbv.x), bf_lo(gbv.y), bf_hi(gbv.y), bf_lo(gbv.z), bf_hi(gbv.z), bf_lo(gbv.w), bf_hi(gbv.w)};
;             float y[8]; float ss = 0.f;
; #pragma unroll
;             for (int e = 0; e < 8; ++e) { y[e] = gbf[e] * (w0[e] * u0[e] + w1[e] * u1[e] + w2[e] * u2[e] + bc[e]); ss += y[e] * y[e]; }
;             const float rstd = 1.0f / sqrtf(wave_sum(ss) * (1.0f / 512.0f) + EPS);
;             u32x4 o;
;             o.x = cvtpk(y[0] * rstd * gc[0], y[1] * rstd * gc[1]); o.y = cvtpk(y[2] * rstd * gc[2], y[3] * rstd * gc[3]);
;             o.z = cvtpk(y[4] * rstd * gc[4], y[5] * rstd * gc[5]); o.w = cvtpk(y[6] * rstd * gc[6], y[7] * rstd * gc[7]);
;             *(GAS u32x4*)(YMIX + ((size_t)b * SEQ + s0 + r) * D + 512 + ch0) = o;
	v_lshlrev_b32_e32 v84, 16, v93
	v_pk_fma_f32 v[102:103], v[40:41], v[82:83], v[102:103]
	v_and_b32_e32 v85, 0xffff0000, v93
	v_pk_add_f32 v[102:103], v[44:45], v[102:103]
	v_and_b32_e32 v97, 0xffff0000, v88
	v_pk_mul_f32 v[102:103], v[102:103], v[84:85]
	v_lshlrev_b32_e32 v84, 16, v96
	v_and_b32_e32 v85, 0xffff0000, v96
	v_lshlrev_b32_e32 v96, 16, v88
	v_lshlrev_b32_e32 v88, 16, v92
	v_and_b32_e32 v89, 0xffff0000, v92
	v_pk_mul_f32 v[92:93], v[34:35], v[100:101]
	v_pk_mul_f32 v[84:85], v[84:85], v[96:97]
	v_pk_fma_f32 v[92:93], v[30:31], v[118:119], v[92:93]
	v_lshlrev_b32_e32 v96, 16, v87
	v_pk_fma_f32 v[92:93], v[38:39], v[84:85], v[92:93]
	v_and_b32_e32 v97, 0xffff0000, v87
	v_pk_add_f32 v[92:93], v[42:43], v[92:93]
	v_lshlrev_b32_e32 v126, 16, v94
	v_pk_mul_f32 v[118:119], v[92:93], v[88:89]
	v_lshlrev_b32_e32 v88, 16, v95
	v_and_b32_e32 v89, 0xffff0000, v95
	v_and_b32_e32 v127, 0xffff0000, v94
	v_lshlrev_b32_e32 v94, 16, v86
	v_and_b32_e32 v95, 0xffff0000, v86
	v_pk_mul_f32 v[88:89], v[88:89], v[96:97]
	v_lshlrev_b32_e32 v96, 16, v91
	v_and_b32_e32 v97, 0xffff0000, v91
	v_pk_mul_f32 v[86:87], v[126:127], v[94:95]
	v_lshlrev_b32_e32 v94, 16, v90
	v_and_b32_e32 v95, 0xffff0000, v90
	v_pk_mul_f32 v[90:91], v[18:19], v[106:107]
	v_pk_fma_f32 v[120:121], v[24:25], v[88:89], v[120:121]
	v_pk_fma_f32 v[90:91], v[14:15], v[124:125], v[90:91]
	v_pk_add_f32 v[120:121], v[28:29], v[120:121]
	v_pk_fma_f32 v[90:91], v[22:23], v[86:87], v[90:91]
	v_pk_mul_f32 v[120:121], v[120:121], v[96:97]
	v_pk_add_f32 v[90:91], v[26:27], v[90:91]
	v_pk_mul_f32 v[96:97], v[120:121], v[120:121]
	v_pk_mul_f32 v[124:125], v[90:91], v[94:95]
	v_pk_mul_f32 v[92:93], v[118:119], v[118:119]
	v_pk_mul_f32 v[90:91], v[124:125], v[124:125]
	v_pk_mul_f32 v[110:111], v[102:103], v[102:103]
	v_add_f32_e32 v90, v90, v91
	v_add_f32_e32 v90, v96, v90
	v_add_f32_e32 v90, v97, v90
	v_add_f32_e32 v90, v92, v90
	v_add_f32_e32 v90, v93, v90
	v_add_f32_e32 v90, v110, v90
	v_add_f32_e32 v90, v111, v90
	v_cmp_class_f32_e32 vcc, v5, v221
	s_waitcnt lgkmcnt(0)
	s_nop 1
	v_add_f32_dpp v90, v90, v90 quad_perm:[1,0,3,2] row_mask:0xf bank_mask:0xf
	v_cndmask_b32_e32 v0, v0, v5, vcc
	v_div_scale_f32 v5, s[4:5], v0, v0, 1.0
	v_rcp_f32_e32 v92, v5
	s_waitcnt lgkmcnt(0)
	s_nop 1
	v_add_f32_dpp v90, v90, v90 quad_perm:[2,3,0,1] row_mask:0xf bank_mask:0xf
	v_add_co_u32_e32 v110, vcc, s41, v2
	v_fma_f32 v93, -v5, v92, 1.0
	s_nop 0
	v_addc_co_u32_e32 v111, vcc, 0, v3, vcc
	v_fmac_f32_e32 v92, v93, v92
	v_div_scale_f32 v93, vcc, 1.0, v0, 1.0
	s_waitcnt lgkmcnt(0)
	s_nop 1
	v_add_f32_dpp v90, v90, v90 row_half_mirror row_mask:0xf bank_mask:0xf
	v_mul_f32_e32 v94, v93, v92
	v_fma_f32 v95, -v5, v94, v93
	v_fmac_f32_e32 v94, v95, v92
	v_fma_f32 v5, -v5, v94, v93
	v_div_fmas_f32 v5, v5, v92, v94
	v_div_fixup_f32 v0, v5, v0, 1.0
	s_waitcnt lgkmcnt(0)
	s_nop 1
	v_add_f32_dpp v5, v90, v90 row_mirror row_mask:0xf bank_mask:0xf
	v_pk_mul_f32 v[90:91], v[140:141], v[0:1] op_sel_hi:[1,0]
	global_store_dwordx4 v[110:111], v[112:115], off offset:1024
	v_pk_mul_f32 v[90:91], v[10:11], v[90:91]
	s_waitcnt vmcnt(8)
	v_and_b32_e32 v93, 0xffff0000, v81
	s_waitcnt lgkmcnt(0)
	v_mov_b32_e32 v92, v5
	v_mov_b32_e32 v253, v5
	s_nop 1
	v_permlane16_swap_b32_e32 v92, v253
	v_add_f32_e32 v5, v92, v253
	v_cvt_pk_bf16_f32 v94, v90, v91
	v_pk_mul_f32 v[90:91], v[116:117], v[0:1] op_sel_hi:[1,0]
	v_pk_mul_f32 v[112:113], v[36:37], v[82:83]
	v_pk_mul_f32 v[90:91], v[12:13], v[90:91]
	s_waitcnt lgkmcnt(0)
	v_mov_b32_e32 v92, v5
	v_mov_b32_e32 v253, v5
	s_nop 1
	v_permlane32_swap_b32_e32 v92, v253
	v_add_f32_e32 v5, v92, v253
	v_fmamk_f32 v5, v5, 0x3b000000, v220
	v_mul_f32_e32 v92, 0x4f800000, v5
	v_cmp_gt_f32_e32 vcc, s45, v5
	v_cvt_pk_bf16_f32 v95, v90, v91
	v_pk_mul_f32 v[90:91], v[108:109], v[0:1] op_sel_hi:[1,0]
	v_cndmask_b32_e32 v5, v5, v92, vcc
	v_sqrt_f32_e32 v92, v5
	v_pk_mul_f32 v[90:91], v[6:7], v[90:91]
	v_pk_fma_f32 v[98:99], v[32:33], v[98:99], v[112:113]
	v_cvt_pk_bf16_f32 v96, v90, v91
	v_pk_mul_f32 v[90:91], v[122:123], v[0:1] op_sel_hi:[1,0]
	v_add_u32_e32 v0, -1, v92
	v_pk_mul_f32 v[108:109], v[8:9], v[90:91]
	v_fma_f32 v90, -v0, v92, v5
	v_cmp_ge_f32_e64 s[4:5], 0, v90
	v_add_u32_e32 v90, 1, v92
	v_fma_f32 v91, -v90, v92, v5
	v_cndmask_b32_e64 v0, v92, v0, s[4:5]
	v_cmp_lt_f32_e64 s[4:5], 0, v91
	v_and_b32_e32 v91, 0xffff0000, v73
	v_lshlrev_b32_e32 v92, 16, v81
	v_cndmask_b32_e64 v0, v0, v90, s[4:5]
	v_mul_f32_e32 v90, 0x37800000, v0
	v_cndmask_b32_e32 v0, v0, v90, vcc
	v_lshlrev_b32_e32 v90, 16, v73
	v_pk_mul_f32 v[90:91], v[90:91], v[92:93]
	s_waitcnt vmcnt(7)
; __device__ __forceinline__ unsigned cvtpk(float lo, float hi) { f32x2 v = {lo, hi}; bf16x2_t b = __builtin_convertvector(v, bf16x2_t); return __builtin_bit_cast(unsigned, b); }
; #define GAS __attribute__((address_space(1)))
; __device__ __forceinline__ float bf_lo(unsigned w) { return __uint_as_float(w << 16); }
; __device__ __forceinline__ float bf_hi(unsigned w) { return __uint_as_float(w & 0xffff0000u); }
; #define CV_U(dst, xv, gv) do { dst[0] = bf_lo(xv.x) * bf_lo(gv.x); dst[1] = bf_hi(xv.x) * bf_hi(gv.x); dst[2] = bf_lo(xv.y) * bf_lo(gv.y); dst[3] = bf_hi(xv.y) * bf_hi(gv.y); \
;         dst[4] = bf_lo(xv.z) * bf_lo(gv.z); dst[5] = bf_hi(xv.z) * bf_hi(gv.z); dst[6] = bf_lo(xv.w) * bf_lo(gv.w); dst[7] = bf_hi(xv.w) * bf_hi(gv.w); } while (0)
; __device__ __forceinline__ void conv_unit(const bf16* PROJ, bf16* YMIX, const float* w_conv, const float* b_conv, const float* g_conv, int b, int c, int wave, int lane_in) {
;     ...
;         for (int r = 0; r < 8; ++r) {
;             float u2[8]; CV_U(u2, xa[r + 2], ga[r + 2]);
;             const u32x4 gbv = gb[r];
;             float gbf[8] = {bf_lo(gbv.x), bf_hi(gbv.x), bf_lo(gbv.y), bf_hi(gbv.y), bf_lo(gbv.z), bf_hi(gbv.z), bf_lo(gbv.w), bf_hi(gbv.w)};
;             float y[8]; float ss = 0.f;
; #pragma unroll
;             for (int e = 0; e < 8; ++e) { y[e] = gbf[e] * (w0[e] * u0[e] + w1[e] * u1[e] + w2[e] * u2[e] + bc[e]); ss += y[e] * y[e]; }
;             const float rstd = 1.0f / sqrtf(wave_sum(ss) * (1.0f / 512.0f) + EPS);
;             u32x4 o;
;             o.x = cvtpk(y[0] * rstd * gc[0], y[1] * rstd * gc[1]); o.y = cvtpk(y[2] * rstd * gc[2], y[3] * rstd * gc[3]);
;             o.z = cvtpk(y[4] * rstd * gc[4], y[5] * rstd * gc[5]); o.w = cvtpk(y[6] * rstd * gc[6], y[7] * rstd * gc[7]);
;             *(GAS u32x4*)(YMIX + ((size_t)b * SEQ + s0 + r) * D + 512 + ch0) = o;
	v_lshlrev_b32_e32 v92, 16, v77
	v_and_b32_e32 v93, 0xffff0000, v77
	v_lshlrev_b32_e32 v112, 16, v72
	v_and_b32_e32 v113, 0xffff0000, v72
	v_lshlrev_b32_e32 v72, 16, v80
	v_and_b32_e32 v73, 0xffff0000, v80
	v_lshlrev_b32_e32 v80, 16, v76
	v_and_b32_e32 v81, 0xffff0000, v76
	v_pk_mul_f32 v[76:77], v[34:35], v[84:85]
	v_pk_mul_f32 v[72:73], v[112:113], v[72:73]
	v_pk_fma_f32 v[76:77], v[30:31], v[100:101], v[76:77]
	v_lshlrev_b32_e32 v112, 16, v79
	v_pk_fma_f32 v[76:77], v[38:39], v[72:73], v[76:77]
	v_and_b32_e32 v113, 0xffff0000, v79
	v_pk_add_f32 v[76:77], v[42:43], v[76:77]
	v_pk_mul_f32 v[114:115], v[20:21], v[88:89]
	v_pk_mul_f32 v[80:81], v[76:77], v[80:81]
	v_lshlrev_b32_e32 v76, 16, v71
	v_and_b32_e32 v77, 0xffff0000, v71
	v_pk_mul_f32 v[76:77], v[76:77], v[112:113]
	v_lshlrev_b32_e32 v112, 16, v75
	v_and_b32_e32 v113, 0xffff0000, v75
	v_pk_fma_f32 v[104:105], v[16:17], v[104:105], v[114:115]
	v_lshlrev_b32_e32 v114, 16, v70
	v_and_b32_e32 v115, 0xffff0000, v70
	v_lshlrev_b32_e32 v70, 16, v78
	v_and_b32_e32 v71, 0xffff0000, v78
	v_lshlrev_b32_e32 v78, 16, v74
	v_and_b32_e32 v79, 0xffff0000, v74
	v_pk_mul_f32 v[74:75], v[18:19], v[86:87]
	v_pk_mul_f32 v[70:71], v[114:115], v[70:71]
	v_pk_fma_f32 v[74:75], v[14:15], v[106:107], v[74:75]
	v_pk_fma_f32 v[104:105], v[24:25], v[76:77], v[104:105]
	v_pk_fma_f32 v[74:75], v[22:23], v[70:71], v[74:75]
	v_pk_add_f32 v[104:105], v[28:29], v[104:105]
	v_pk_add_f32 v[74:75], v[26:27], v[74:75]
	v_pk_mul_f32 v[104:105], v[104:105], v[112:113]
	v_pk_mul_f32 v[106:107], v[74:75], v[78:79]
	v_pk_mul_f32 v[112:113], v[104:105], v[104:105]
	v_pk_mul_f32 v[74:75], v[106:107], v[106:107]
	v_pk_fma_f32 v[98:99], v[40:41], v[90:91], v[98:99]
	v_add_f32_e32 v74, v74, v75
	v_add_f32_e32 v74, v112, v74
	v_pk_add_f32 v[98:99], v[44:45], v[98:99]
	v_pk_mul_f32 v[100:101], v[80:81], v[80:81]
	v_add_f32_e32 v74, v113, v74
	v_pk_mul_f32 v[92:93], v[98:99], v[92:93]
	v_add_f32_e32 v74, v100, v74
	v_pk_mul_f32 v[98:99], v[92:93], v[92:93]
	v_add_f32_e32 v74, v101, v74
	v_add_f32_e32 v74, v98, v74
	v_add_f32_e32 v74, v99, v74
	v_cmp_class_f32_e32 vcc, v5, v221
	v_cvt_pk_bf16_f32 v97, v108, v109
	global_store_dwordx4 v[110:111], v[94:97], off offset:3072
	v_cndmask_b32_e32 v0, v0, v5, vcc
	v_div_scale_f32 v5, s[4:5], v0, v0, 1.0
	s_waitcnt lgkmcnt(0)
	s_nop 1
	v_add_f32_dpp v74, v74, v74 quad_perm:[1,0,3,2] row_mask:0xf bank_mask:0xf
	v_rcp_f32_e32 v116, v5
	v_lshlrev_b32_e32 v98, 16, v61
	v_and_b32_e32 v99, 0xffff0000, v61
	v_fma_f32 v78, -v5, v116, 1.0
	v_fmac_f32_e32 v116, v78, v116
	v_div_scale_f32 v78, vcc, 1.0, v0, 1.0
	s_waitcnt lgkmcnt(0)
	s_nop 1
	v_add_f32_dpp v74, v74, v74 quad_perm:[2,3,0,1] row_mask:0xf bank_mask:0xf
	v_mul_f32_e32 v79, v78, v116
	v_fma_f32 v94, -v5, v79, v78
	v_fmac_f32_e32 v79, v94, v116
	v_fma_f32 v5, -v5, v79, v78
	v_div_fmas_f32 v5, v5, v116, v79
	v_div_fixup_f32 v0, v5, v0, 1.0
	s_waitcnt lgkmcnt(0)
	s_nop 1
	v_add_f32_dpp v5, v74, v74 row_half_mirror row_mask:0xf bank_mask:0xf
	v_pk_mul_f32 v[74:75], v[124:125], v[0:1] op_sel_hi:[1,0]
	v_pk_mul_f32 v[100:101], v[36:37], v[90:91]
	v_pk_mul_f32 v[74:75], v[10:11], v[74:75]
	v_pk_fma_f32 v[82:83], v[32:33], v[82:83], v[100:101]
	s_waitcnt lgkmcnt(0)
	s_nop 1
	v_add_f32_dpp v5, v5, v5 row_mirror row_mask:0xf bank_mask:0xf
	v_cvt_pk_bf16_f32 v94, v74, v75
	v_pk_mul_f32 v[74:75], v[120:121], v[0:1] op_sel_hi:[1,0]
	s_waitcnt vmcnt(7)
	v_lshlrev_b32_e32 v100, 16, v68
	v_pk_mul_f32 v[74:75], v[12:13], v[74:75]
	s_waitcnt lgkmcnt(0)
	v_mov_b32_e32 v78, v5
	v_mov_b32_e32 v253, v5
	s_nop 1
	v_permlane16_swap_b32_e32 v78, v253
	v_add_f32_e32 v5, v78, v253
	v_cvt_pk_bf16_f32 v95, v74, v75
	v_pk_mul_f32 v[74:75], v[118:119], v[0:1] op_sel_hi:[1,0]
	v_and_b32_e32 v101, 0xffff0000, v68
	v_pk_mul_f32 v[74:75], v[6:7], v[74:75]
	v_lshlrev_b32_e32 v68, 16, v60
	v_cvt_pk_bf16_f32 v96, v74, v75
	v_pk_mul_f32 v[74:75], v[102:103], v[0:1] op_sel_hi:[1,0]
	s_waitcnt lgkmcnt(0)
	v_mov_b32_e32 v78, v5
	v_mov_b32_e32 v253, v5
	s_nop 1
	v_permlane32_swap_b32_e32 v78, v253
	v_add_f32_e32 v0, v78, v253
	v_fmamk_f32 v0, v0, 0x3b000000, v220
	v_mul_f32_e32 v5, 0x4f800000, v0
	v_cmp_gt_f32_e32 vcc, s45, v0
	v_pk_mul_f32 v[74:75], v[8:9], v[74:75]
	s_waitcnt vmcnt(6)
	v_and_b32_e32 v61, 0xffff0000, v64
	v_cndmask_b32_e32 v0, v0, v5, vcc
	v_sqrt_f32_e32 v5, v0
	v_cvt_pk_bf16_f32 v97, v74, v75
	v_add_co_u32_e64 v74, s[4:5], s47, v2
	v_add_u32_e32 v78, -1, v5
	s_nop 0
	v_addc_co_u32_e64 v75, s[4:5], 0, v3, s[4:5]
	v_fma_f32 v79, -v78, v5, v0
	v_cmp_ge_f32_e64 s[4:5], 0, v79
	v_add_u32_e32 v79, 1, v5
	v_pk_mul_f32 v[102:103], v[20:21], v[76:77]
	v_cndmask_b32_e64 v78, v5, v78, s[4:5]
	v_fma_f32 v5, -v79, v5, v0
	v_cmp_lt_f32_e64 s[4:5], 0, v5
	v_pk_fma_f32 v[88:89], v[16:17], v[88:89], v[102:103]
	v_lshlrev_b32_e32 v102, 16, v66
	v_cndmask_b32_e64 v5, v78, v79, s[4:5]
	v_mul_f32_e32 v78, 0x37800000, v5
	v_cndmask_b32_e32 v5, v5, v78, vcc
	v_lshlrev_b32_e32 v78, 16, v69
	v_and_b32_e32 v79, 0xffff0000, v69
	v_pk_mul_f32 v[98:99], v[78:79], v[98:99]
	v_lshlrev_b32_e32 v78, 16, v65
	v_and_b32_e32 v79, 0xffff0000, v65
	v_and_b32_e32 v69, 0xffff0000, v60
	v_lshlrev_b32_e32 v60, 16, v64
	v_pk_mul_f32 v[64:65], v[34:35], v[72:73]
	v_pk_mul_f32 v[68:69], v[100:101], v[68:69]
	v_pk_fma_f32 v[64:65], v[30:31], v[84:85], v[64:65]
	v_lshlrev_b32_e32 v84, 16, v67
	v_and_b32_e32 v85, 0xffff0000, v67
	v_lshlrev_b32_e32 v100, 16, v59
	v_and_b32_e32 v101, 0xffff0000, v59
	v_pk_mul_f32 v[84:85], v[84:85], v[100:101]
	v_lshlrev_b32_e32 v100, 16, v63
	v_and_b32_e32 v101, 0xffff0000, v63
	v_and_b32_e32 v103, 0xffff0000, v66
	v_lshlrev_b32_e32 v66, 16, v58
	v_and_b32_e32 v67, 0xffff0000, v58
	v_lshlrev_b32_e32 v58, 16, v62
	v_and_b32_e32 v59, 0xffff0000, v62
	v_pk_mul_f32 v[62:63], v[18:19], v[70:71]
	v_pk_mul_f32 v[66:67], v[102:103], v[66:67]
	v_pk_fma_f32 v[62:63], v[14:15], v[86:87], v[62:63]
	v_pk_fma_f32 v[88:89], v[24:25], v[84:85], v[88:89]
	v_pk_fma_f32 v[62:63], v[22:23], v[66:67], v[62:63]
	v_pk_add_f32 v[88:89], v[28:29], v[88:89]
	v_pk_add_f32 v[62:63], v[26:27], v[62:63]
	v_cmp_class_f32_e32 vcc, v0, v221
	v_pk_mul_f32 v[62:63], v[62:63], v[58:59]
	v_pk_fma_f32 v[64:65], v[38:39], v[68:69], v[64:65]
	v_pk_mul_f32 v[88:89], v[88:89], v[100:101]
	v_pk_mul_f32 v[58:59], v[62:63], v[62:63]
	v_cndmask_b32_e32 v0, v5, v0, vcc
	v_pk_add_f32 v[64:65], v[42:43], v[64:65]
	v_pk_mul_f32 v[100:101], v[88:89], v[88:89]
	v_add_f32_e32 v5, v58, v59
	v_pk_fma_f32 v[82:83], v[40:41], v[98:99], v[82:83]
	v_pk_mul_f32 v[64:65], v[64:65], v[60:61]
	v_add_f32_e32 v5, v100, v5
	v_pk_add_f32 v[82:83], v[44:45], v[82:83]
	v_pk_mul_f32 v[60:61], v[64:65], v[64:65]
	v_add_f32_e32 v5, v101, v5
	v_pk_mul_f32 v[78:79], v[82:83], v[78:79]
	v_add_f32_e32 v5, v60, v5
	v_pk_mul_f32 v[82:83], v[78:79], v[78:79]
	v_add_f32_e32 v5, v61, v5
	v_add_f32_e32 v5, v82, v5
	v_add_f32_e32 v5, v83, v5
	v_div_scale_f32 v59, s[4:5], v0, v0, 1.0
	v_rcp_f32_e32 v60, v59
	v_pk_mul_f32 v[36:37], v[36:37], v[98:99]
	s_waitcnt lgkmcnt(0)
; __device__ __forceinline__ unsigned cvtpk(float lo, float hi) { f32x2 v = {lo, hi}; bf16x2_t b = __builtin_convertvector(v, bf16x2_t); return __builtin_bit_cast(unsigned, b); }
; #define GAS __attribute__((address_space(1)))
; __device__ __forceinline__ float bf_lo(unsigned w) { return __uint_as_float(w << 16); }
; __device__ __forceinline__ float bf_hi(unsigned w) { return __uint_as_float(w & 0xffff0000u); }
; #define CV_U(dst, xv, gv) do { dst[0] = bf_lo(xv.x) * bf_lo(gv.x); dst[1] = bf_hi(xv.x) * bf_hi(gv.x); dst[2] = bf_lo(xv.y) * bf_lo(gv.y); dst[3] = bf_hi(xv.y) * bf_hi(gv.y); \
;         dst[4] = bf_lo(xv.z) * bf_lo(gv.z); dst[5] = bf_hi(xv.z) * bf_hi(gv.z); dst[6] = bf_lo(xv.w) * bf_lo(gv.w); dst[7] = bf_hi(xv.w) * bf_hi(gv.w); } while (0)
; __device__ __forceinline__ void conv_unit(const bf16* PROJ, bf16* YMIX, const float* w_conv, const float* b_conv, const float* g_conv, int b, int c, int wave, int lane_in) {
;     ...
;         for (int r = 0; r < 8; ++r) {
;             float u2[8]; CV_U(u2, xa[r + 2], ga[r + 2]);
;             const u32x4 gbv = gb[r];
;             float gbf[8] = {bf_lo(gbv.x), bf_hi(gbv.x), bf_lo(gbv.y), bf_hi(gbv.y), bf_lo(gbv.z), bf_hi(gbv.z), bf_lo(gbv.w), bf_hi(gbv.w)};
;             float y[8]; float ss = 0.f;
; #pragma unroll
;             for (int e = 0; e < 8; ++e) { y[e] = gbf[e] * (w0[e] * u0[e] + w1[e] * u1[e] + w2[e] * u2[e] + bc[e]); ss += y[e] * y[e]; }
;             const float rstd = 1.0f / sqrtf(wave_sum(ss) * (1.0f / 512.0f) + EPS);
;             u32x4 o;
;             o.x = cvtpk(y[0] * rstd * gc[0], y[1] * rstd * gc[1]); o.y = cvtpk(y[2] * rstd * gc[2], y[3] * rstd * gc[3]);
;             o.z = cvtpk(y[4] * rstd * gc[4], y[5] * rstd * gc[5]); o.w = cvtpk(y[6] * rstd * gc[6], y[7] * rstd * gc[7]);
;             *(GAS u32x4*)(YMIX + ((size_t)b * SEQ + s0 + r) * D + 512 + ch0) = o;
	s_nop 1
	v_add_f32_dpp v5, v5, v5 quad_perm:[1,0,3,2] row_mask:0xf bank_mask:0xf
	v_fma_f32 v61, -v59, v60, 1.0
	v_fmac_f32_e32 v60, v61, v60
	v_div_scale_f32 v61, vcc, 1.0, v0, 1.0
	s_waitcnt lgkmcnt(0)
	s_nop 1
	v_add_f32_dpp v5, v5, v5 quad_perm:[2,3,0,1] row_mask:0xf bank_mask:0xf
	v_mul_f32_e32 v82, v61, v60
	v_fma_f32 v83, -v59, v82, v61
	v_fmac_f32_e32 v82, v83, v60
	v_fma_f32 v59, -v59, v82, v61
	s_waitcnt lgkmcnt(0)
	s_nop 1
	v_add_f32_dpp v5, v5, v5 row_half_mirror row_mask:0xf bank_mask:0xf
	v_div_fmas_f32 v58, v59, v60, v82
	v_div_fixup_f32 v0, v58, v0, 1.0
	v_pk_mul_f32 v[58:59], v[106:107], v[0:1] op_sel_hi:[1,0]
	s_waitcnt vmcnt(5)
	v_and_b32_e32 v83, 0xffff0000, v57
	s_waitcnt lgkmcnt(0)
	s_nop 1
	v_add_f32_dpp v5, v5, v5 row_mirror row_mask:0xf bank_mask:0xf
	v_pk_mul_f32 v[60:61], v[104:105], v[0:1] op_sel_hi:[1,0]
	v_pk_mul_f32 v[58:59], v[10:11], v[58:59]
	v_pk_mul_f32 v[60:61], v[12:13], v[60:61]
	v_cvt_pk_bf16_f32 v58, v58, v59
	s_waitcnt lgkmcnt(0)
	v_mov_b32_e32 v82, v5
	v_mov_b32_e32 v253, v5
	s_nop 1
	v_permlane16_swap_b32_e32 v82, v253
	v_add_f32_e32 v5, v82, v253
	v_cvt_pk_bf16_f32 v59, v60, v61
	v_pk_mul_f32 v[60:61], v[80:81], v[0:1] op_sel_hi:[1,0]
	v_pk_mul_f32 v[80:81], v[92:93], v[0:1] op_sel_hi:[1,0]
	v_pk_mul_f32 v[60:61], v[6:7], v[60:61]
	s_waitcnt lgkmcnt(0)
	v_mov_b32_e32 v82, v5
	v_mov_b32_e32 v253, v5
	s_nop 1
	v_permlane32_swap_b32_e32 v82, v253
	v_add_f32_e32 v5, v82, v253
	v_fmamk_f32 v5, v5, 0x3b000000, v220
	v_cvt_pk_bf16_f32 v60, v60, v61
	v_mul_f32_e32 v61, 0x4f800000, v5
	v_cmp_gt_f32_e32 vcc, s45, v5
	v_pk_mul_f32 v[80:81], v[8:9], v[80:81]
	v_pk_fma_f32 v[32:33], v[32:33], v[90:91], v[36:37]
	v_cndmask_b32_e32 v5, v5, v61, vcc
	v_sqrt_f32_e32 v82, v5
	v_cvt_pk_bf16_f32 v61, v80, v81
	v_pk_mul_f32 v[34:35], v[34:35], v[68:69]
	v_pk_mul_f32 v[20:21], v[20:21], v[84:85]
	v_add_u32_e32 v0, -1, v82
	v_fma_f32 v80, -v0, v82, v5
	v_cmp_ge_f32_e64 s[4:5], 0, v80
	v_add_u32_e32 v80, 1, v82
	v_fma_f32 v81, -v80, v82, v5
	v_cndmask_b32_e64 v0, v82, v0, s[4:5]
	v_cmp_lt_f32_e64 s[4:5], 0, v81
	v_and_b32_e32 v81, 0xffff0000, v49
	v_lshlrev_b32_e32 v82, 16, v57
	v_cndmask_b32_e64 v0, v0, v80, s[4:5]
	v_mul_f32_e32 v80, 0x37800000, v0
	v_cndmask_b32_e32 v0, v0, v80, vcc
	v_lshlrev_b32_e32 v80, 16, v49
	v_pk_mul_f32 v[80:81], v[82:83], v[80:81]
	v_pk_fma_f32 v[30:31], v[30:31], v[72:73], v[34:35]
	v_pk_fma_f32 v[32:33], v[40:41], v[80:81], v[32:33]
	v_lshlrev_b32_e32 v40, 16, v48
	v_pk_add_f32 v[32:33], v[44:45], v[32:33]
	v_and_b32_e32 v41, 0xffff0000, v48
	v_lshlrev_b32_e32 v44, 16, v56
	v_and_b32_e32 v45, 0xffff0000, v56
	v_pk_mul_f32 v[40:41], v[44:45], v[40:41]
	v_pk_fma_f32 v[16:17], v[16:17], v[76:77], v[20:21]
	v_pk_fma_f32 v[30:31], v[38:39], v[40:41], v[30:31]
	v_lshlrev_b32_e32 v38, 16, v47
	v_and_b32_e32 v39, 0xffff0000, v47
	v_lshlrev_b32_e32 v40, 16, v55
	v_and_b32_e32 v41, 0xffff0000, v55
	v_pk_mul_f32 v[38:39], v[40:41], v[38:39]
	v_pk_mul_f32 v[18:19], v[18:19], v[66:67]
	v_pk_fma_f32 v[16:17], v[24:25], v[38:39], v[16:17]
	v_lshlrev_b32_e32 v24, 16, v46
	v_pk_add_f32 v[16:17], v[28:29], v[16:17]
	v_and_b32_e32 v25, 0xffff0000, v46
	v_lshlrev_b32_e32 v28, 16, v54
	v_and_b32_e32 v29, 0xffff0000, v54
	v_pk_mul_f32 v[24:25], v[28:29], v[24:25]
	v_pk_fma_f32 v[14:15], v[14:15], v[70:71], v[18:19]
	s_waitcnt vmcnt(4)
	v_lshlrev_b32_e32 v28, 16, v50
	v_pk_fma_f32 v[14:15], v[22:23], v[24:25], v[14:15]
	v_and_b32_e32 v29, 0xffff0000, v50
	v_pk_add_f32 v[14:15], v[26:27], v[14:15]
	v_lshlrev_b32_e32 v40, 16, v51
	v_and_b32_e32 v41, 0xffff0000, v51
	v_pk_mul_f32 v[18:19], v[14:15], v[28:29]
	v_cmp_class_f32_e32 vcc, v5, v221
	v_pk_mul_f32 v[20:21], v[16:17], v[40:41]
	v_pk_mul_f32 v[14:15], v[18:19], v[18:19]
	v_cndmask_b32_e32 v0, v0, v5, vcc
	v_lshlrev_b32_e32 v44, 16, v52
	v_and_b32_e32 v45, 0xffff0000, v52
	v_pk_add_f32 v[30:31], v[42:43], v[30:31]
	v_pk_mul_f32 v[16:17], v[20:21], v[20:21]
	v_add_f32_e32 v5, v14, v15
	v_pk_mul_f32 v[30:31], v[30:31], v[44:45]
	v_add_f32_e32 v5, v16, v5
	v_lshlrev_b32_e32 v82, 16, v53
	v_and_b32_e32 v83, 0xffff0000, v53
	v_pk_mul_f32 v[34:35], v[30:31], v[30:31]
	v_add_f32_e32 v5, v17, v5
	v_pk_mul_f32 v[32:33], v[32:33], v[82:83]
	v_add_f32_e32 v5, v34, v5
	v_pk_mul_f32 v[36:37], v[32:33], v[32:33]
	v_add_f32_e32 v5, v35, v5
	v_add_f32_e32 v5, v36, v5
	v_add_f32_e32 v5, v37, v5
	v_div_scale_f32 v15, s[4:5], v0, v0, 1.0
	v_rcp_f32_e32 v16, v15
	global_store_dwordx4 v[74:75], v[94:97], off offset:1024
	s_waitcnt lgkmcnt(0)
; __device__ __forceinline__ unsigned cvtpk(float lo, float hi) { f32x2 v = {lo, hi}; bf16x2_t b = __builtin_convertvector(v, bf16x2_t); return __builtin_bit_cast(unsigned, b); }
; #define GAS __attribute__((address_space(1)))
; __device__ __forceinline__ float bf_lo(unsigned w) { return __uint_as_float(w << 16); }
; __device__ __forceinline__ float bf_hi(unsigned w) { return __uint_as_float(w & 0xffff0000u); }
; #define CV_U(dst, xv, gv) do { dst[0] = bf_lo(xv.x) * bf_lo(gv.x); dst[1] = bf_hi(xv.x) * bf_hi(gv.x); dst[2] = bf_lo(xv.y) * bf_lo(gv.y); dst[3] = bf_hi(xv.y) * bf_hi(gv.y); \
;         dst[4] = bf_lo(xv.z) * bf_lo(gv.z); dst[5] = bf_hi(xv.z) * bf_hi(gv.z); dst[6] = bf_lo(xv.w) * bf_lo(gv.w); dst[7] = bf_hi(xv.w) * bf_hi(gv.w); } while (0)
; __device__ __forceinline__ void conv_unit(const bf16* PROJ, bf16* YMIX, const float* w_conv, const float* b_conv, const float* g_conv, int b, int c, int wave, int lane_in) {
;     ...
;         for (int r = 0; r < 8; ++r) {
;             float u2[8]; CV_U(u2, xa[r + 2], ga[r + 2]);
;             const u32x4 gbv = gb[r];
;             float gbf[8] = {bf_lo(gbv.x), bf_hi(gbv.x), bf_lo(gbv.y), bf_hi(gbv.y), bf_lo(gbv.z), bf_hi(gbv.z), bf_lo(gbv.w), bf_hi(gbv.w)};
;             float y[8]; float ss = 0.f;
; #pragma unroll
;             for (int e = 0; e < 8; ++e) { y[e] = gbf[e] * (w0[e] * u0[e] + w1[e] * u1[e] + w2[e] * u2[e] + bc[e]); ss += y[e] * y[e]; }
;             const float rstd = 1.0f / sqrtf(wave_sum(ss) * (1.0f / 512.0f) + EPS);
;             u32x4 o;
;             o.x = cvtpk(y[0] * rstd * gc[0], y[1] * rstd * gc[1]); o.y = cvtpk(y[2] * rstd * gc[2], y[3] * rstd * gc[3]);
;             o.z = cvtpk(y[4] * rstd * gc[4], y[5] * rstd * gc[5]); o.w = cvtpk(y[6] * rstd * gc[6], y[7] * rstd * gc[7]);
;             *(GAS u32x4*)(YMIX + ((size_t)b * SEQ + s0 + r) * D + 512 + ch0) = o;
	s_nop 1
	v_add_f32_dpp v5, v5, v5 quad_perm:[1,0,3,2] row_mask:0xf bank_mask:0xf
	v_fma_f32 v17, -v15, v16, 1.0
	v_fmac_f32_e32 v16, v17, v16
	v_div_scale_f32 v17, vcc, 1.0, v0, 1.0
	s_waitcnt lgkmcnt(0)
	s_nop 1
	v_add_f32_dpp v5, v5, v5 quad_perm:[2,3,0,1] row_mask:0xf bank_mask:0xf
	v_mul_f32_e32 v22, v17, v16
	v_fma_f32 v23, -v15, v22, v17
	v_fmac_f32_e32 v22, v23, v16
	v_fma_f32 v15, -v15, v22, v17
	s_waitcnt lgkmcnt(0)
	s_nop 1
	v_add_f32_dpp v5, v5, v5 row_half_mirror row_mask:0xf bank_mask:0xf
	v_div_fmas_f32 v14, v15, v16, v22
	v_div_fixup_f32 v0, v14, v0, 1.0
	v_pk_mul_f32 v[14:15], v[62:63], v[0:1] op_sel_hi:[1,0]
	global_store_dwordx4 v[74:75], v[58:61], off offset:3072
	s_waitcnt lgkmcnt(0)
	s_nop 1
	v_add_f32_dpp v5, v5, v5 row_mirror row_mask:0xf bank_mask:0xf
	v_pk_mul_f32 v[16:17], v[88:89], v[0:1] op_sel_hi:[1,0]
	v_pk_mul_f32 v[14:15], v[10:11], v[14:15]
	v_pk_mul_f32 v[16:17], v[12:13], v[16:17]
	v_cvt_pk_bf16_f32 v14, v14, v15
	s_waitcnt lgkmcnt(0)
	v_mov_b32_e32 v22, v5
	v_mov_b32_e32 v253, v5
	s_nop 1
	v_permlane16_swap_b32_e32 v22, v253
	v_add_f32_e32 v5, v22, v253
	v_cvt_pk_bf16_f32 v15, v16, v17
	v_pk_mul_f32 v[16:17], v[64:65], v[0:1] op_sel_hi:[1,0]
	s_waitcnt lgkmcnt(0)
	v_mov_b32_e32 v22, v5
	v_mov_b32_e32 v253, v5
	s_nop 1
	v_permlane32_swap_b32_e32 v22, v253
	v_add_f32_e32 v5, v22, v253
	v_pk_mul_f32 v[16:17], v[6:7], v[16:17]
	v_fmamk_f32 v5, v5, 0x3b000000, v220
	v_cvt_pk_bf16_f32 v16, v16, v17
	v_mul_f32_e32 v17, 0x4f800000, v5
	v_cmp_gt_f32_e32 vcc, s45, v5
	v_pk_mul_f32 v[22:23], v[78:79], v[0:1] op_sel_hi:[1,0]
	s_nop 0
	v_cndmask_b32_e32 v5, v5, v17, vcc
	v_sqrt_f32_e32 v24, v5
	v_pk_mul_f32 v[22:23], v[8:9], v[22:23]
	v_add_u32_e32 v0, -1, v24
	v_cvt_pk_bf16_f32 v17, v22, v23
	v_fma_f32 v22, -v0, v24, v5
	v_cmp_ge_f32_e64 s[4:5], 0, v22
	v_add_u32_e32 v22, 1, v24
	v_fma_f32 v23, -v22, v24, v5
	v_cndmask_b32_e64 v0, v24, v0, s[4:5]
	v_cmp_lt_f32_e64 s[4:5], 0, v23
	s_nop 1
	v_cndmask_b32_e64 v0, v0, v22, s[4:5]
	v_mul_f32_e32 v22, 0x37800000, v0
	v_cndmask_b32_e32 v0, v0, v22, vcc
	v_cmp_class_f32_e32 vcc, v5, v221
	s_nop 1
	v_cndmask_b32_e32 v0, v0, v5, vcc
	v_div_scale_f32 v5, s[4:5], v0, v0, 1.0
	v_rcp_f32_e32 v22, v5
	v_add_co_u32_e32 v2, vcc, s39, v2
	s_add_i32 s4, s10, 1
	s_nop 0
	v_addc_co_u32_e32 v3, vcc, 0, v3, vcc
	global_store_dwordx4 v[2:3], v[14:17], off offset:1024
	s_cmp_ge_i32 s10, s35
	s_mov_b32 s10, s4
	v_fma_f32 v14, -v5, v22, 1.0
	v_fmac_f32_e32 v22, v14, v22
	v_div_scale_f32 v14, vcc, 1.0, v0, 1.0
	v_mul_f32_e32 v15, v14, v22
	v_fma_f32 v16, -v5, v15, v14
	v_fmac_f32_e32 v15, v16, v22
	v_fma_f32 v5, -v5, v15, v14
	v_div_fmas_f32 v5, v5, v22, v15
	v_div_fixup_f32 v0, v5, v0, 1.0
	v_pk_mul_f32 v[14:15], v[18:19], v[0:1] op_sel_hi:[1,0]
	s_nop 0
	v_pk_mul_f32 v[10:11], v[10:11], v[14:15]
	v_pk_mul_f32 v[14:15], v[20:21], v[0:1] op_sel_hi:[1,0]
	v_cvt_pk_bf16_f32 v10, v10, v11
	v_pk_mul_f32 v[12:13], v[12:13], v[14:15]
	s_nop 0
	v_cvt_pk_bf16_f32 v11, v12, v13
	v_pk_mul_f32 v[12:13], v[30:31], v[0:1] op_sel_hi:[1,0]
	s_nop 0
	v_pk_mul_f32 v[6:7], v[6:7], v[12:13]
	s_nop 0
	v_cvt_pk_bf16_f32 v12, v6, v7
	v_pk_mul_f32 v[6:7], v[32:33], v[0:1] op_sel_hi:[1,0]
	s_nop 0
	v_pk_mul_f32 v[6:7], v[8:9], v[6:7]
	s_nop 0
	v_cvt_pk_bf16_f32 v13, v6, v7
	global_store_dwordx4 v[2:3], v[10:13], off offset:3072
	s_cbranch_scc1 .LBB0_546
